# baseline (speedup 1.0000x reference)
; __device__ __forceinline__ unsigned xb_ld(unsigned* p)              { return __hip_atomic_load(p, __ATOMIC_RELAXED, __HIP_MEMORY_SCOPE_AGENT); }
; __device__ __forceinline__ unsigned xb_add(unsigned* p, unsigned v) { return __hip_atomic_fetch_add(p, v, __ATOMIC_RELAXED, __HIP_MEMORY_SCOPE_AGENT); }
; #define XB_SPIN(cond, bar) do { unsigned _sp = 0; while (cond) { __builtin_amdgcn_s_sleep(1); \
;     if ((++_sp & 255u) == 0u) { if (xb_ld(&(bar)[XB_TMO])) break; if (_sp > XB_SPIN_CAP) { atomicAdd(&(bar)[XB_TMO], 1u); break; } } } } while (0)
; __device__ __forceinline__ void xcd_barrier() {
;     ...
;     const unsigned bx = st[0], nloc = st[1], nx = st[2];
;     __builtin_amdgcn_s_waitcnt(0);
;     const unsigned old = xb_add(&bar[XB_XSUB(bx)], 1u);
;     const unsigned gen = old / nloc;
;     if (old + 1u == (gen + 1u) * nloc) {
;       __builtin_amdgcn_fence(__ATOMIC_RELEASE, "agent");
;       asm volatile("s_waitcnt vmcnt(0)" ::: "memory");
;       const unsigned og = xb_add(&bar[XB_TOP], 1u);
;       const unsigned tg = og / nx;
;       if (og + 1u == (tg + 1u) * nx) xb_add(&bar[XB_TOPGEN], 1u);
;       else XB_SPIN(xb_ld(&bar[XB_TOPGEN]) == tg, bar);
;       __builtin_amdgcn_fence(__ATOMIC_ACQUIRE, "agent");
;       xb_add(&bar[XB_XGEN(bx)], 1u);
;     } else {
;       XB_SPIN(xb_ld(&bar[XB_XGEN(bx)]) == gen, bar);
;       __builtin_amdgcn_fence(__ATOMIC_ACQUIRE, "agent");
;     }
.LBB0_44:
	s_or_b64 exec, exec, s[10:11]
	v_cvt_f32_u32_e32 v6, v3
	s_waitcnt vmcnt(0)
	v_readfirstlane_b32 s8, v2
	v_sub_u32_e32 v2, 0, v3
	v_rcp_iflag_f32_e32 v6, v6
	v_add_u32_e32 v5, s8, v5
	v_mul_f32_e32 v6, 0x4f7ffffe, v6
	v_cvt_u32_f32_e32 v6, v6
	v_mul_lo_u32 v2, v2, v6
	v_mul_hi_u32 v2, v6, v2
	v_add_u32_e32 v2, v6, v2
	v_mul_hi_u32 v2, v5, v2
	v_mul_lo_u32 v6, v2, v3
	v_sub_u32_e32 v6, v5, v6
	v_add_u32_e32 v7, 1, v2
	v_cmp_ge_u32_e32 vcc, v6, v3
	v_add_u32_e32 v5, 1, v5
	s_nop 0
	v_cndmask_b32_e32 v2, v2, v7, vcc
	v_sub_u32_e32 v7, v6, v3
	v_cndmask_b32_e32 v6, v6, v7, vcc
	v_add_u32_e32 v7, 1, v2
	v_cmp_ge_u32_e32 vcc, v6, v3
	s_nop 1
	v_cndmask_b32_e32 v2, v2, v7, vcc
	v_mul_lo_u32 v6, v3, v2
	v_add_u32_e32 v3, v6, v3
	v_cmp_ne_u32_e32 vcc, v5, v3
	s_and_saveexec_b64 s[8:9], vcc
	s_xor_b64 s[8:9], exec, s[8:9]
	s_cbranch_execz .LBB0_58
	s_movk_i32 s10, 0xd40
	s_mov_b32 s11, 0
	s_lshl_b64 s[10:11], s[10:11], 2
	s_add_u32 s14, s3, s10
	s_addc_u32 s15, s26, s11
	v_mov_b32_e32 v3, 0
	global_load_dword v4, v3, s[14:15] sc1
	s_waitcnt vmcnt(0)
	v_cmp_eq_u32_e32 vcc, v4, v2
	s_and_saveexec_b64 s[10:11], vcc
	s_cbranch_execz .LBB0_57
	s_add_u32 s12, s6, 0xfc00200
	s_addc_u32 s13, s7, 0
	s_mov_b32 s28, 1
	s_mov_b64 s[16:17], 0
	s_branch .LBB0_48

; __device__ __forceinline__ unsigned xb_ld(unsigned* p)              { return __hip_atomic_load(p, __ATOMIC_RELAXED, __HIP_MEMORY_SCOPE_AGENT); }
; __device__ __forceinline__ unsigned xb_add(unsigned* p, unsigned v) { return __hip_atomic_fetch_add(p, v, __ATOMIC_RELAXED, __HIP_MEMORY_SCOPE_AGENT); }
; #define XB_SPIN(cond, bar) do { unsigned _sp = 0; while (cond) { __builtin_amdgcn_s_sleep(1); \
;     if ((++_sp & 255u) == 0u) { if (xb_ld(&(bar)[XB_TMO])) break; if (_sp > XB_SPIN_CAP) { atomicAdd(&(bar)[XB_TMO], 1u); break; } } } } while (0)
; __device__ __forceinline__ void xcd_barrier() {
;     ...
;     const unsigned bx = st[0], nloc = st[1], nx = st[2];
;     __builtin_amdgcn_s_waitcnt(0);
;     const unsigned old = xb_add(&bar[XB_XSUB(bx)], 1u);
;     const unsigned gen = old / nloc;
;     if (old + 1u == (gen + 1u) * nloc) {
;       __builtin_amdgcn_fence(__ATOMIC_RELEASE, "agent");
;       asm volatile("s_waitcnt vmcnt(0)" ::: "memory");
;       const unsigned og = xb_add(&bar[XB_TOP], 1u);
;       const unsigned tg = og / nx;
;       if (og + 1u == (tg + 1u) * nx) xb_add(&bar[XB_TOPGEN], 1u);
;       else XB_SPIN(xb_ld(&bar[XB_TOPGEN]) == tg, bar);
;       __builtin_amdgcn_fence(__ATOMIC_ACQUIRE, "agent");
;       xb_add(&bar[XB_XGEN(bx)], 1u);
;     } else {
;       XB_SPIN(xb_ld(&bar[XB_XGEN(bx)]) == gen, bar);
;       __builtin_amdgcn_fence(__ATOMIC_ACQUIRE, "agent");
;     }
.LBB0_667:
	s_or_b64 exec, exec, s[10:11]
	v_cvt_f32_u32_e32 v5, v3
	s_waitcnt vmcnt(0)
	v_readfirstlane_b32 s8, v2
	v_sub_u32_e32 v2, 0, v3
	v_rcp_iflag_f32_e32 v5, v5
	v_add_u32_e32 v6, s8, v1
	v_mul_f32_e32 v5, 0x4f7ffffe, v5
	v_cvt_u32_f32_e32 v5, v5
	v_mul_lo_u32 v1, v2, v5
	v_mul_hi_u32 v1, v5, v1
	v_add_u32_e32 v1, v5, v1
	v_mul_hi_u32 v1, v6, v1
	v_mul_lo_u32 v2, v1, v3
	v_sub_u32_e32 v2, v6, v2
	v_add_u32_e32 v5, 1, v1
	v_cmp_ge_u32_e32 vcc, v2, v3
	s_nop 1
	v_cndmask_b32_e32 v1, v1, v5, vcc
	v_sub_u32_e32 v5, v2, v3
	v_cndmask_b32_e32 v2, v2, v5, vcc
	v_add_u32_e32 v5, 1, v1
	v_cmp_ge_u32_e32 vcc, v2, v3
	v_add_u32_e32 v2, 1, v6
	s_nop 0
	v_cndmask_b32_e32 v1, v1, v5, vcc
	v_mul_lo_u32 v5, v3, v1
	v_add_u32_e32 v3, v5, v3
	v_cmp_ne_u32_e32 vcc, v2, v3
	s_and_saveexec_b64 s[8:9], vcc
	s_xor_b64 s[8:9], exec, s[8:9]
	s_cbranch_execz .LBB0_681
	s_movk_i32 s10, 0xd40
	s_mov_b32 s11, 0
	s_lshl_b64 s[10:11], s[10:11], 2
	s_add_u32 s14, s3, s10
	s_addc_u32 s15, s26, s11
	v_mov_b32_e32 v2, 0
	global_load_dword v3, v2, s[14:15] sc1
	s_waitcnt vmcnt(0)
	v_cmp_eq_u32_e32 vcc, v3, v1
	s_and_saveexec_b64 s[10:11], vcc
	s_cbranch_execz .LBB0_680
	s_add_u32 s12, s6, 0xfc00200
	s_addc_u32 s13, s7, 0
	s_mov_b32 s28, 1
	s_mov_b64 s[16:17], 0
	s_branch .LBB0_671
